# EpiSwiGLU float section regenerated with plain (non-packed) f32 VALU: tests packed-f32 issue cost in a no-MFMA epilogue
# speedup vs baseline: 1.0021x; 1.0021x over previous
; __device__ __forceinline__ u32x4 pack8(f32x4 a, f32x4 b) { u32x4 w; w.x = pk2(a[0], a[1]); w.y = pk2(a[2], a[3]); w.z = pk2(b[0], b[1]); w.w = pk2(b[2], b[3]); return w; }
; __device__ __forceinline__ float fast_sigmoid(float x) { return __builtin_amdgcn_rcpf(1.0f + __builtin_amdgcn_exp2f(-x * LOG2E)); }
;     __device__ __forceinline__ void operator()(const Acc& acc, const Unit& u, int wr, int wc, int fr, int fq, const RsCtx& rc) const {
;         const int col = u.pn * 128 + wc * 32 + 8 * fq;
; #pragma unroll
;         for (int ai = 0; ai < 2; ++ai)
; #pragma unroll
;             for (int m = 0; m < 4; ++m) { const int row = EPI_ROW(u, ai, wr, m, fr); const float rs = rc.get(u.pm, ai * 128 + wr * 64 + m * 16 + fr, row);
;                 f32x4 a0 = acc[ai][0][m][0] * rs, a1 = acc[ai][0][m][1] * rs; const f32x4 b0 = acc[ai][1][m][0] * rs, b1 = acc[ai][1][m][1] * rs;
; #pragma unroll
;                 for (int e = 0; e < 4; ++e) { a0[e] = a0[e] * fast_sigmoid(a0[e]) * b0[e]; a1[e] = a1[e] * fast_sigmoid(a1[e]) * b1[e]; }
;                 *(u32x4*)(O + (size_t)row * FF + col) = pack8(a0, a1);
.LBB0_155:
	s_waitcnt lgkmcnt(0)
	v_lshl_or_b32 v140, s36, 7, v148
	v_readlane_b32 s6, v255, 0
	v_ashrrev_i32_e32 v141, 31, v140
	v_readlane_b32 s7, v255, 1
	v_lshl_add_u64 v[140:141], v[140:141], 1, s[6:7]
	s_mov_b64 s[28:29], -1
	s_andn2_b64 vcc, exec, s[24:25]
	s_mov_b32 s100, 0xbfb8aa3b
	v_mul_f32_e32 v126, v144, v126
	v_mul_f32_e32 v127, v144, v127
	v_mul_f32_e32 v128, v144, v128
	v_mul_f32_e32 v129, v144, v129
	v_mul_f32_e32 v122, v144, v122
	v_mul_f32_e32 v123, v144, v123
	v_mul_f32_e32 v124, v144, v124
	v_mul_f32_e32 v125, v144, v125
	v_mul_f32_e32 v150, s100, v126
	v_mul_f32_e32 v151, s100, v127
	v_mul_f32_e32 v152, s100, v128
	v_mul_f32_e32 v153, s100, v129
	v_mul_f32_e32 v154, s100, v122
	v_mul_f32_e32 v155, s100, v123
	v_mul_f32_e32 v156, s100, v124
	v_mul_f32_e32 v157, s100, v125
	v_exp_f32_e32 v150, v150
	v_exp_f32_e32 v151, v151
	v_exp_f32_e32 v152, v152
	v_exp_f32_e32 v153, v153
	v_exp_f32_e32 v154, v154
	v_exp_f32_e32 v155, v155
	v_exp_f32_e32 v156, v156
	v_exp_f32_e32 v157, v157
	v_mul_f32_e32 v118, v144, v118
	v_mul_f32_e32 v119, v144, v119
	v_mul_f32_e32 v120, v144, v120
	v_mul_f32_e32 v121, v144, v121
	v_mul_f32_e32 v114, v144, v114
	v_mul_f32_e32 v115, v144, v115
	v_mul_f32_e32 v116, v144, v116
	v_mul_f32_e32 v117, v144, v117
	v_add_f32_e32 v150, 1.0, v150
	v_add_f32_e32 v151, 1.0, v151
	v_add_f32_e32 v152, 1.0, v152
	v_add_f32_e32 v153, 1.0, v153
	v_add_f32_e32 v154, 1.0, v154
	v_add_f32_e32 v155, 1.0, v155
	v_add_f32_e32 v156, 1.0, v156
	v_add_f32_e32 v157, 1.0, v157
	v_rcp_f32_e32 v150, v150
	v_rcp_f32_e32 v151, v151
	v_rcp_f32_e32 v152, v152
	v_rcp_f32_e32 v153, v153
	v_rcp_f32_e32 v154, v154
	v_rcp_f32_e32 v155, v155
	v_rcp_f32_e32 v156, v156
	v_rcp_f32_e32 v157, v157
	v_mul_f32_e32 v126, v126, v150
	v_mul_f32_e32 v127, v127, v151
	v_mul_f32_e32 v128, v128, v152
	v_mul_f32_e32 v129, v129, v153
	v_mul_f32_e32 v122, v122, v154
	v_mul_f32_e32 v123, v123, v155
	v_mul_f32_e32 v124, v124, v156
	v_mul_f32_e32 v125, v125, v157
	v_mul_f32_e32 v118, v118, v126
	v_mul_f32_e32 v119, v119, v127
	v_mul_f32_e32 v120, v120, v128
	v_mul_f32_e32 v121, v121, v129
	v_mul_f32_e32 v122, v114, v122
	v_mul_f32_e32 v123, v115, v123
	v_mul_f32_e32 v124, v116, v124
	v_mul_f32_e32 v125, v117, v125
	v_cvt_pk_bf16_f32 v114, v118, v119
	v_cvt_pk_bf16_f32 v115, v120, v121
	v_cvt_pk_bf16_f32 v116, v122, v123
	v_cvt_pk_bf16_f32 v117, v124, v125
	v_mad_i64_i32 v[118:119], s[6:7], v142, s64, v[140:141]
	flat_store_dwordx4 v[118:119], v[114:117]
	s_nop 1
	v_cndmask_b32_e64 v115, 0, 1, s[24:25]
	v_or_b32_e32 v114, 16, v142
	v_cmp_ne_u32_e64 s[6:7], 1, v115
	s_cbranch_vccnz .LBB0_161
	s_cmp_eq_u32 s48, s12
	s_mov_b64 s[24:25], -1
	s_cbranch_scc1 .LBB0_158
	v_ashrrev_i32_e32 v115, 31, v114
	v_lshlrev_b64 v[116:117], 6, v[114:115]
	v_lshl_add_u64 v[128:129], s[38:39], 0, v[116:117]
	flat_load_dwordx4 v[116:119], v[128:129]
	flat_load_dwordx4 v[120:123], v[128:129] offset:16
	flat_load_dwordx4 v[124:127], v[128:129] offset:32
	flat_load_dwordx4 v[150:153], v[128:129] offset:48
	s_mov_b64 s[24:25], 0
	s_waitcnt vmcnt(0) lgkmcnt(0)
	v_mov_b32_e32 v128, v117
	v_mov_b32_e32 v129, v118
	v_mov_b32_e32 v117, v119
	v_mov_b32_e32 v118, v121
	v_mov_b32_e32 v119, v122
	v_mov_b32_e32 v121, v123
	v_pk_add_f32 v[116:117], v[128:129], v[116:117]
	v_pk_add_f32 v[118:119], v[118:119], v[120:121]
	v_pk_add_f32 v[116:117], v[116:117], v[116:117] op_sel:[0,1] op_sel_hi:[1,0]
	v_pk_add_f32 v[118:119], v[118:119], v[118:119] op_sel:[0,1] op_sel_hi:[1,0]
	v_add_f32_e32 v120, v124, v125
	v_add_f32_e32 v122, v126, v127
	v_mov_b32_e32 v117, v150
	v_mov_b32_e32 v119, v151
	v_mov_b32_e32 v121, v152
	v_mov_b32_e32 v123, v153
	v_pk_add_f32 v[116:117], v[116:117], v[118:119]
	v_pk_add_f32 v[118:119], v[120:121], v[122:123]
	s_nop 0
	v_pk_add_f32 v[116:117], v[116:117], v[118:119]
	s_nop 0
	v_add_f32_e32 v115, v116, v117
	v_fmamk_f32 v115, v115, 0x3a800000, v205
	v_cmp_gt_f32_e32 vcc, s77, v115
	v_mul_f32_e32 v116, 0x4b800000, v115
	s_nop 0
	v_cndmask_b32_e32 v115, v115, v116, vcc
	v_rsq_f32_e32 v115, v115
	s_nop 0
	v_mul_f32_e32 v116, 0x45800000, v115
	v_cndmask_b32_e32 v116, v115, v116, vcc

; __device__ __forceinline__ u32x4 pack8(f32x4 a, f32x4 b) { u32x4 w; w.x = pk2(a[0], a[1]); w.y = pk2(a[2], a[3]); w.z = pk2(b[0], b[1]); w.w = pk2(b[2], b[3]); return w; }
; __device__ __forceinline__ float fast_sigmoid(float x) { return __builtin_amdgcn_rcpf(1.0f + __builtin_amdgcn_exp2f(-x * LOG2E)); }
;     __device__ __forceinline__ void operator()(const Acc& acc, const Unit& u, int wr, int wc, int fr, int fq, const RsCtx& rc) const {
;     ...
;             for (int m = 0; m < 4; ++m) { const int row = EPI_ROW(u, ai, wr, m, fr); const float rs = rc.get(u.pm, ai * 128 + wr * 64 + m * 16 + fr, row);
;                 f32x4 a0 = acc[ai][0][m][0] * rs, a1 = acc[ai][0][m][1] * rs; const f32x4 b0 = acc[ai][1][m][0] * rs, b1 = acc[ai][1][m][1] * rs;
; #pragma unroll
;                 for (int e = 0; e < 4; ++e) { a0[e] = a0[e] * fast_sigmoid(a0[e]) * b0[e]; a1[e] = a1[e] * fast_sigmoid(a1[e]) * b1[e]; }
;                 *(u32x4*)(O + (size_t)row * FF + col) = pack8(a0, a1);
.LBB0_163:
	s_waitcnt lgkmcnt(0)
	s_and_b64 vcc, exec, s[6:7]
	s_mov_b32 s100, 0xbfb8aa3b
	v_mul_f32_e32 v110, v116, v110
	v_mul_f32_e32 v111, v116, v111
	v_mul_f32_e32 v112, v116, v112
	v_mul_f32_e32 v113, v116, v113
	v_mul_f32_e32 v106, v116, v106
	v_mul_f32_e32 v107, v116, v107
	v_mul_f32_e32 v108, v116, v108
	v_mul_f32_e32 v109, v116, v109
	v_mul_f32_e32 v118, s100, v110
	v_mul_f32_e32 v119, s100, v111
	v_mul_f32_e32 v120, s100, v112
	v_mul_f32_e32 v121, s100, v113
	v_mul_f32_e32 v122, s100, v106
	v_mul_f32_e32 v123, s100, v107
	v_mul_f32_e32 v124, s100, v108
	v_mul_f32_e32 v125, s100, v109
	v_exp_f32_e32 v118, v118
	v_exp_f32_e32 v119, v119
	v_exp_f32_e32 v120, v120
	v_exp_f32_e32 v121, v121
	v_exp_f32_e32 v122, v122
	v_exp_f32_e32 v123, v123
	v_exp_f32_e32 v124, v124
	v_exp_f32_e32 v125, v125
	v_mul_f32_e32 v102, v116, v102
	v_mul_f32_e32 v103, v116, v103
	v_mul_f32_e32 v104, v116, v104
	v_mul_f32_e32 v105, v116, v105
	v_mul_f32_e32 v98, v116, v98
	v_mul_f32_e32 v99, v116, v99
	v_mul_f32_e32 v100, v116, v100
	v_mul_f32_e32 v101, v116, v101
	v_add_f32_e32 v118, 1.0, v118
	v_add_f32_e32 v119, 1.0, v119
	v_add_f32_e32 v120, 1.0, v120
	v_add_f32_e32 v121, 1.0, v121
	v_add_f32_e32 v122, 1.0, v122
	v_add_f32_e32 v123, 1.0, v123
	v_add_f32_e32 v124, 1.0, v124
	v_add_f32_e32 v125, 1.0, v125
	v_rcp_f32_e32 v118, v118
	v_rcp_f32_e32 v119, v119
	v_rcp_f32_e32 v120, v120
	v_rcp_f32_e32 v121, v121
	v_rcp_f32_e32 v122, v122
	v_rcp_f32_e32 v123, v123
	v_rcp_f32_e32 v124, v124
	v_rcp_f32_e32 v125, v125
	v_mul_f32_e32 v110, v110, v118
	v_mul_f32_e32 v111, v111, v119
	v_mul_f32_e32 v112, v112, v120
	v_mul_f32_e32 v113, v113, v121
	v_mul_f32_e32 v106, v106, v122
	v_mul_f32_e32 v107, v107, v123
	v_mul_f32_e32 v108, v108, v124
	v_mul_f32_e32 v109, v109, v125
	v_mul_f32_e32 v102, v102, v110
	v_mul_f32_e32 v103, v103, v111
	v_mul_f32_e32 v104, v104, v112
	v_mul_f32_e32 v105, v105, v113
	v_mul_f32_e32 v106, v98, v106
	v_mul_f32_e32 v107, v99, v107
	v_mul_f32_e32 v108, v100, v108
	v_mul_f32_e32 v109, v101, v109
	v_cvt_pk_bf16_f32 v98, v102, v103
	v_cvt_pk_bf16_f32 v99, v104, v105
	v_cvt_pk_bf16_f32 v100, v106, v107
	v_cvt_pk_bf16_f32 v101, v108, v109
	v_mad_i64_i32 v[102:103], s[24:25], v114, s64, v[140:141]
	flat_store_dwordx4 v[102:103], v[98:101]
	s_mov_b64 s[24:25], -1
	s_nop 0
	v_or_b32_e32 v98, 32, v142
	s_cbranch_vccnz .LBB0_169
	s_cmp_eq_u32 s48, s12
	s_cbranch_scc1 .LBB0_166
	v_ashrrev_i32_e32 v99, 31, v98
	v_lshlrev_b64 v[100:101], 6, v[98:99]
	v_lshl_add_u64 v[112:113], s[38:39], 0, v[100:101]
	flat_load_dwordx4 v[100:103], v[112:113]
	flat_load_dwordx4 v[104:107], v[112:113] offset:16
	flat_load_dwordx4 v[108:111], v[112:113] offset:32
	s_nop 0
	flat_load_dwordx4 v[112:115], v[112:113] offset:48
	s_mov_b64 s[24:25], 0
	s_waitcnt vmcnt(0) lgkmcnt(0)
	v_mov_b32_e32 v116, v101
	v_mov_b32_e32 v117, v102
	v_mov_b32_e32 v101, v103
	v_mov_b32_e32 v102, v105
	v_mov_b32_e32 v103, v106
	v_mov_b32_e32 v105, v107
	v_pk_add_f32 v[100:101], v[116:117], v[100:101]
	v_pk_add_f32 v[102:103], v[102:103], v[104:105]
	v_pk_add_f32 v[100:101], v[100:101], v[100:101] op_sel:[0,1] op_sel_hi:[1,0]
	v_pk_add_f32 v[102:103], v[102:103], v[102:103] op_sel:[0,1] op_sel_hi:[1,0]
	v_add_f32_e32 v104, v108, v109
	v_add_f32_e32 v106, v110, v111
	v_mov_b32_e32 v101, v112
	v_mov_b32_e32 v103, v113
	v_mov_b32_e32 v105, v114
	v_mov_b32_e32 v107, v115
	v_pk_add_f32 v[100:101], v[100:101], v[102:103]
	v_pk_add_f32 v[102:103], v[104:105], v[106:107]
	s_nop 0
	v_pk_add_f32 v[100:101], v[100:101], v[102:103]
	s_nop 0
	v_add_f32_e32 v99, v100, v101
	v_fmamk_f32 v99, v99, 0x3a800000, v205
	v_cmp_gt_f32_e32 vcc, s77, v99
	v_mul_f32_e32 v100, 0x4b800000, v99
	s_nop 0
	v_cndmask_b32_e32 v99, v99, v100, vcc
	v_rsq_f32_e32 v99, v99
	s_nop 0
	v_mul_f32_e32 v100, 0x45800000, v99
	v_cndmask_b32_e32 v100, v99, v100, vcc

; __device__ __forceinline__ u32x4 pack8(f32x4 a, f32x4 b) { u32x4 w; w.x = pk2(a[0], a[1]); w.y = pk2(a[2], a[3]); w.z = pk2(b[0], b[1]); w.w = pk2(b[2], b[3]); return w; }
; __device__ __forceinline__ float fast_sigmoid(float x) { return __builtin_amdgcn_rcpf(1.0f + __builtin_amdgcn_exp2f(-x * LOG2E)); }
;     __device__ __forceinline__ void operator()(const Acc& acc, const Unit& u, int wr, int wc, int fr, int fq, const RsCtx& rc) const {
;     ...
;             for (int m = 0; m < 4; ++m) { const int row = EPI_ROW(u, ai, wr, m, fr); const float rs = rc.get(u.pm, ai * 128 + wr * 64 + m * 16 + fr, row);
;                 f32x4 a0 = acc[ai][0][m][0] * rs, a1 = acc[ai][0][m][1] * rs; const f32x4 b0 = acc[ai][1][m][0] * rs, b1 = acc[ai][1][m][1] * rs;
; #pragma unroll
;                 for (int e = 0; e < 4; ++e) { a0[e] = a0[e] * fast_sigmoid(a0[e]) * b0[e]; a1[e] = a1[e] * fast_sigmoid(a1[e]) * b1[e]; }
;                 *(u32x4*)(O + (size_t)row * FF + col) = pack8(a0, a1);
.LBB0_171:
	s_waitcnt lgkmcnt(0)
	s_and_b64 vcc, exec, s[6:7]
	s_mov_b32 s100, 0xbfb8aa3b
	v_mul_f32_e32 v94, v100, v94
	v_mul_f32_e32 v95, v100, v95
	v_mul_f32_e32 v96, v100, v96
	v_mul_f32_e32 v97, v100, v97
	v_mul_f32_e32 v90, v100, v90
	v_mul_f32_e32 v91, v100, v91
	v_mul_f32_e32 v92, v100, v92
	v_mul_f32_e32 v93, v100, v93
	v_mul_f32_e32 v102, s100, v94
	v_mul_f32_e32 v103, s100, v95
	v_mul_f32_e32 v104, s100, v96
	v_mul_f32_e32 v105, s100, v97
	v_mul_f32_e32 v106, s100, v90
	v_mul_f32_e32 v107, s100, v91
	v_mul_f32_e32 v108, s100, v92
	v_mul_f32_e32 v109, s100, v93
	v_exp_f32_e32 v102, v102
	v_exp_f32_e32 v103, v103
	v_exp_f32_e32 v104, v104
	v_exp_f32_e32 v105, v105
	v_exp_f32_e32 v106, v106
	v_exp_f32_e32 v107, v107
	v_exp_f32_e32 v108, v108
	v_exp_f32_e32 v109, v109
	v_mul_f32_e32 v86, v100, v86
	v_mul_f32_e32 v87, v100, v87
	v_mul_f32_e32 v88, v100, v88
	v_mul_f32_e32 v89, v100, v89
	v_mul_f32_e32 v82, v100, v82
	v_mul_f32_e32 v83, v100, v83
	v_mul_f32_e32 v84, v100, v84
	v_mul_f32_e32 v85, v100, v85
	v_add_f32_e32 v102, 1.0, v102
	v_add_f32_e32 v103, 1.0, v103
	v_add_f32_e32 v104, 1.0, v104
	v_add_f32_e32 v105, 1.0, v105
	v_add_f32_e32 v106, 1.0, v106
	v_add_f32_e32 v107, 1.0, v107
	v_add_f32_e32 v108, 1.0, v108
	v_add_f32_e32 v109, 1.0, v109
	v_rcp_f32_e32 v102, v102
	v_rcp_f32_e32 v103, v103
	v_rcp_f32_e32 v104, v104
	v_rcp_f32_e32 v105, v105
	v_rcp_f32_e32 v106, v106
	v_rcp_f32_e32 v107, v107
	v_rcp_f32_e32 v108, v108
	v_rcp_f32_e32 v109, v109
	v_mul_f32_e32 v94, v94, v102
	v_mul_f32_e32 v95, v95, v103
	v_mul_f32_e32 v96, v96, v104
	v_mul_f32_e32 v97, v97, v105
	v_mul_f32_e32 v90, v90, v106
	v_mul_f32_e32 v91, v91, v107
	v_mul_f32_e32 v92, v92, v108
	v_mul_f32_e32 v93, v93, v109
	v_mul_f32_e32 v86, v86, v94
	v_mul_f32_e32 v87, v87, v95
	v_mul_f32_e32 v88, v88, v96
	v_mul_f32_e32 v89, v89, v97
	v_mul_f32_e32 v90, v82, v90
	v_mul_f32_e32 v91, v83, v91
	v_mul_f32_e32 v92, v84, v92
	v_mul_f32_e32 v93, v85, v93
	v_cvt_pk_bf16_f32 v82, v86, v87
	v_cvt_pk_bf16_f32 v83, v88, v89
	v_cvt_pk_bf16_f32 v84, v90, v91
	v_cvt_pk_bf16_f32 v85, v92, v93
	v_mad_i64_i32 v[86:87], s[24:25], v98, s64, v[140:141]
	flat_store_dwordx4 v[86:87], v[82:85]
	s_mov_b64 s[24:25], -1
	s_nop 0
	v_or_b32_e32 v82, 48, v142
	s_cbranch_vccnz .LBB0_177
	s_cmp_eq_u32 s48, s12
	s_cbranch_scc1 .LBB0_174
	v_ashrrev_i32_e32 v83, 31, v82
	v_lshlrev_b64 v[84:85], 6, v[82:83]
	v_lshl_add_u64 v[96:97], s[38:39], 0, v[84:85]
	flat_load_dwordx4 v[84:87], v[96:97]
	flat_load_dwordx4 v[88:91], v[96:97] offset:16
	flat_load_dwordx4 v[92:95], v[96:97] offset:32
	s_nop 0
	flat_load_dwordx4 v[96:99], v[96:97] offset:48
	s_mov_b64 s[24:25], 0
	s_waitcnt vmcnt(0) lgkmcnt(0)
	v_mov_b32_e32 v100, v85
	v_mov_b32_e32 v101, v86
	v_mov_b32_e32 v85, v87
	v_mov_b32_e32 v86, v89
	v_mov_b32_e32 v87, v90
	v_mov_b32_e32 v89, v91
	v_pk_add_f32 v[84:85], v[100:101], v[84:85]
	v_pk_add_f32 v[86:87], v[86:87], v[88:89]
	v_pk_add_f32 v[84:85], v[84:85], v[84:85] op_sel:[0,1] op_sel_hi:[1,0]
	v_pk_add_f32 v[86:87], v[86:87], v[86:87] op_sel:[0,1] op_sel_hi:[1,0]
	v_add_f32_e32 v88, v92, v93
	v_add_f32_e32 v90, v94, v95
	v_mov_b32_e32 v85, v96
	v_mov_b32_e32 v87, v97
	v_mov_b32_e32 v89, v98
	v_mov_b32_e32 v91, v99
	v_pk_add_f32 v[84:85], v[84:85], v[86:87]
	v_pk_add_f32 v[86:87], v[88:89], v[90:91]
	s_nop 0
	v_pk_add_f32 v[84:85], v[84:85], v[86:87]
	s_nop 0
	v_add_f32_e32 v83, v84, v85
	v_fmamk_f32 v83, v83, 0x3a800000, v205
	v_cmp_gt_f32_e32 vcc, s77, v83
	v_mul_f32_e32 v84, 0x4b800000, v83
	s_nop 0
	v_cndmask_b32_e32 v83, v83, v84, vcc
	v_rsq_f32_e32 v83, v83
	s_nop 0
	v_mul_f32_e32 v84, 0x45800000, v83
	v_cndmask_b32_e32 v84, v83, v84, vcc

; __device__ __forceinline__ u32x4 pack8(f32x4 a, f32x4 b) { u32x4 w; w.x = pk2(a[0], a[1]); w.y = pk2(a[2], a[3]); w.z = pk2(b[0], b[1]); w.w = pk2(b[2], b[3]); return w; }
; __device__ __forceinline__ float fast_sigmoid(float x) { return __builtin_amdgcn_rcpf(1.0f + __builtin_amdgcn_exp2f(-x * LOG2E)); }
;     __device__ __forceinline__ void operator()(const Acc& acc, const Unit& u, int wr, int wc, int fr, int fq, const RsCtx& rc) const {
;     ...
;             for (int m = 0; m < 4; ++m) { const int row = EPI_ROW(u, ai, wr, m, fr); const float rs = rc.get(u.pm, ai * 128 + wr * 64 + m * 16 + fr, row);
;                 f32x4 a0 = acc[ai][0][m][0] * rs, a1 = acc[ai][0][m][1] * rs; const f32x4 b0 = acc[ai][1][m][0] * rs, b1 = acc[ai][1][m][1] * rs;
; #pragma unroll
;                 for (int e = 0; e < 4; ++e) { a0[e] = a0[e] * fast_sigmoid(a0[e]) * b0[e]; a1[e] = a1[e] * fast_sigmoid(a1[e]) * b1[e]; }
;                 *(u32x4*)(O + (size_t)row * FF + col) = pack8(a0, a1);
.LBB0_179:
	s_waitcnt lgkmcnt(0)
	s_and_b64 vcc, exec, s[6:7]
	s_mov_b32 s100, 0xbfb8aa3b
	v_mul_f32_e32 v78, v84, v78
	v_mul_f32_e32 v79, v84, v79
	v_mul_f32_e32 v80, v84, v80
	v_mul_f32_e32 v81, v84, v81
	v_mul_f32_e32 v74, v84, v74
	v_mul_f32_e32 v75, v84, v75
	v_mul_f32_e32 v76, v84, v76
	v_mul_f32_e32 v77, v84, v77
	v_mul_f32_e32 v86, s100, v78
	v_mul_f32_e32 v87, s100, v79
	v_mul_f32_e32 v88, s100, v80
	v_mul_f32_e32 v89, s100, v81
	v_mul_f32_e32 v90, s100, v74
	v_mul_f32_e32 v91, s100, v75
	v_mul_f32_e32 v92, s100, v76
	v_mul_f32_e32 v93, s100, v77
	v_exp_f32_e32 v86, v86
	v_exp_f32_e32 v87, v87
	v_exp_f32_e32 v88, v88
	v_exp_f32_e32 v89, v89
	v_exp_f32_e32 v90, v90
	v_exp_f32_e32 v91, v91
	v_exp_f32_e32 v92, v92
	v_exp_f32_e32 v93, v93
	v_mul_f32_e32 v70, v84, v70
	v_mul_f32_e32 v71, v84, v71
	v_mul_f32_e32 v72, v84, v72
	v_mul_f32_e32 v73, v84, v73
	v_mul_f32_e32 v66, v84, v66
	v_mul_f32_e32 v67, v84, v67
	v_mul_f32_e32 v68, v84, v68
	v_mul_f32_e32 v69, v84, v69
	v_add_f32_e32 v86, 1.0, v86
	v_add_f32_e32 v87, 1.0, v87
	v_add_f32_e32 v88, 1.0, v88
	v_add_f32_e32 v89, 1.0, v89
	v_add_f32_e32 v90, 1.0, v90
	v_add_f32_e32 v91, 1.0, v91
	v_add_f32_e32 v92, 1.0, v92
	v_add_f32_e32 v93, 1.0, v93
	v_rcp_f32_e32 v86, v86
	v_rcp_f32_e32 v87, v87
	v_rcp_f32_e32 v88, v88
	v_rcp_f32_e32 v89, v89
	v_rcp_f32_e32 v90, v90
	v_rcp_f32_e32 v91, v91
	v_rcp_f32_e32 v92, v92
	v_rcp_f32_e32 v93, v93
	v_mul_f32_e32 v78, v78, v86
	v_mul_f32_e32 v79, v79, v87
	v_mul_f32_e32 v80, v80, v88
	v_mul_f32_e32 v81, v81, v89
	v_mul_f32_e32 v74, v74, v90
	v_mul_f32_e32 v75, v75, v91
	v_mul_f32_e32 v76, v76, v92
	v_mul_f32_e32 v77, v77, v93
	v_mul_f32_e32 v70, v70, v78
	v_mul_f32_e32 v71, v71, v79
	v_mul_f32_e32 v72, v72, v80
	v_mul_f32_e32 v73, v73, v81
	v_mul_f32_e32 v74, v66, v74
	v_mul_f32_e32 v75, v67, v75
	v_mul_f32_e32 v76, v68, v76
	v_mul_f32_e32 v77, v69, v77
	v_cvt_pk_bf16_f32 v66, v70, v71
	v_cvt_pk_bf16_f32 v67, v72, v73
	v_cvt_pk_bf16_f32 v68, v74, v75
	v_cvt_pk_bf16_f32 v69, v76, v77
	v_mad_i64_i32 v[70:71], s[24:25], v82, s64, v[140:141]
	flat_store_dwordx4 v[70:71], v[66:69]
	s_mov_b64 s[24:25], -1
	s_nop 0
	v_add_u32_e32 v66, 0x80, v142
	s_cbranch_vccnz .LBB0_185
	s_cmp_eq_u32 s48, s12
	s_cbranch_scc1 .LBB0_182
	v_ashrrev_i32_e32 v67, 31, v66
	v_lshlrev_b64 v[68:69], 6, v[66:67]
	v_lshl_add_u64 v[80:81], s[38:39], 0, v[68:69]
	flat_load_dwordx4 v[68:71], v[80:81]
	flat_load_dwordx4 v[72:75], v[80:81] offset:16
	flat_load_dwordx4 v[76:79], v[80:81] offset:32
	s_nop 0
	flat_load_dwordx4 v[80:83], v[80:81] offset:48
	s_mov_b64 s[24:25], 0
	s_waitcnt vmcnt(0) lgkmcnt(0)
	v_mov_b32_e32 v84, v69
	v_mov_b32_e32 v85, v70
	v_mov_b32_e32 v69, v71
	v_mov_b32_e32 v70, v73
	v_mov_b32_e32 v71, v74
	v_mov_b32_e32 v73, v75
	v_pk_add_f32 v[68:69], v[84:85], v[68:69]
	v_pk_add_f32 v[70:71], v[70:71], v[72:73]
	v_pk_add_f32 v[68:69], v[68:69], v[68:69] op_sel:[0,1] op_sel_hi:[1,0]
	v_pk_add_f32 v[70:71], v[70:71], v[70:71] op_sel:[0,1] op_sel_hi:[1,0]
	v_add_f32_e32 v72, v76, v77
	v_add_f32_e32 v74, v78, v79
	v_mov_b32_e32 v69, v80
	v_mov_b32_e32 v71, v81
	v_mov_b32_e32 v73, v82
	v_mov_b32_e32 v75, v83
	v_pk_add_f32 v[68:69], v[68:69], v[70:71]
	v_pk_add_f32 v[70:71], v[72:73], v[74:75]
	s_nop 0
	v_pk_add_f32 v[68:69], v[68:69], v[70:71]
	s_nop 0
	v_add_f32_e32 v67, v68, v69
	v_fmamk_f32 v67, v67, 0x3a800000, v205
	v_cmp_gt_f32_e32 vcc, s77, v67
	v_mul_f32_e32 v68, 0x4b800000, v67
	s_nop 0
	v_cndmask_b32_e32 v67, v67, v68, vcc
	v_rsq_f32_e32 v67, v67
	s_nop 0
	v_mul_f32_e32 v68, 0x45800000, v67
	v_cndmask_b32_e32 v68, v67, v68, vcc

; __device__ __forceinline__ u32x4 pack8(f32x4 a, f32x4 b) { u32x4 w; w.x = pk2(a[0], a[1]); w.y = pk2(a[2], a[3]); w.z = pk2(b[0], b[1]); w.w = pk2(b[2], b[3]); return w; }
; __device__ __forceinline__ float fast_sigmoid(float x) { return __builtin_amdgcn_rcpf(1.0f + __builtin_amdgcn_exp2f(-x * LOG2E)); }
;     __device__ __forceinline__ void operator()(const Acc& acc, const Unit& u, int wr, int wc, int fr, int fq, const RsCtx& rc) const {
;     ...
;             for (int m = 0; m < 4; ++m) { const int row = EPI_ROW(u, ai, wr, m, fr); const float rs = rc.get(u.pm, ai * 128 + wr * 64 + m * 16 + fr, row);
;                 f32x4 a0 = acc[ai][0][m][0] * rs, a1 = acc[ai][0][m][1] * rs; const f32x4 b0 = acc[ai][1][m][0] * rs, b1 = acc[ai][1][m][1] * rs;
; #pragma unroll
;                 for (int e = 0; e < 4; ++e) { a0[e] = a0[e] * fast_sigmoid(a0[e]) * b0[e]; a1[e] = a1[e] * fast_sigmoid(a1[e]) * b1[e]; }
;                 *(u32x4*)(O + (size_t)row * FF + col) = pack8(a0, a1);
.LBB0_187:
	s_waitcnt lgkmcnt(0)
	s_and_b64 vcc, exec, s[6:7]
	s_mov_b32 s100, 0xbfb8aa3b
	v_mul_f32_e32 v62, v68, v62
	v_mul_f32_e32 v63, v68, v63
	v_mul_f32_e32 v64, v68, v64
	v_mul_f32_e32 v65, v68, v65
	v_mul_f32_e32 v58, v68, v58
	v_mul_f32_e32 v59, v68, v59
	v_mul_f32_e32 v60, v68, v60
	v_mul_f32_e32 v61, v68, v61
	v_mul_f32_e32 v70, s100, v62
	v_mul_f32_e32 v71, s100, v63
	v_mul_f32_e32 v72, s100, v64
	v_mul_f32_e32 v73, s100, v65
	v_mul_f32_e32 v74, s100, v58
	v_mul_f32_e32 v75, s100, v59
	v_mul_f32_e32 v76, s100, v60
	v_mul_f32_e32 v77, s100, v61
	v_exp_f32_e32 v70, v70
	v_exp_f32_e32 v71, v71
	v_exp_f32_e32 v72, v72
	v_exp_f32_e32 v73, v73
	v_exp_f32_e32 v74, v74
	v_exp_f32_e32 v75, v75
	v_exp_f32_e32 v76, v76
	v_exp_f32_e32 v77, v77
	v_mul_f32_e32 v54, v68, v54
	v_mul_f32_e32 v55, v68, v55
	v_mul_f32_e32 v56, v68, v56
	v_mul_f32_e32 v57, v68, v57
	v_mul_f32_e32 v50, v68, v50
	v_mul_f32_e32 v51, v68, v51
	v_mul_f32_e32 v52, v68, v52
	v_mul_f32_e32 v53, v68, v53
	v_add_f32_e32 v70, 1.0, v70
	v_add_f32_e32 v71, 1.0, v71
	v_add_f32_e32 v72, 1.0, v72
	v_add_f32_e32 v73, 1.0, v73
	v_add_f32_e32 v74, 1.0, v74
	v_add_f32_e32 v75, 1.0, v75
	v_add_f32_e32 v76, 1.0, v76
	v_add_f32_e32 v77, 1.0, v77
	v_rcp_f32_e32 v70, v70
	v_rcp_f32_e32 v71, v71
	v_rcp_f32_e32 v72, v72
	v_rcp_f32_e32 v73, v73
	v_rcp_f32_e32 v74, v74
	v_rcp_f32_e32 v75, v75
	v_rcp_f32_e32 v76, v76
	v_rcp_f32_e32 v77, v77
	v_mul_f32_e32 v62, v62, v70
	v_mul_f32_e32 v63, v63, v71
	v_mul_f32_e32 v64, v64, v72
	v_mul_f32_e32 v65, v65, v73
	v_mul_f32_e32 v58, v58, v74
	v_mul_f32_e32 v59, v59, v75
	v_mul_f32_e32 v60, v60, v76
	v_mul_f32_e32 v61, v61, v77
	v_mul_f32_e32 v54, v54, v62
	v_mul_f32_e32 v55, v55, v63
	v_mul_f32_e32 v56, v56, v64
	v_mul_f32_e32 v57, v57, v65
	v_mul_f32_e32 v58, v50, v58
	v_mul_f32_e32 v59, v51, v59
	v_mul_f32_e32 v60, v52, v60
	v_mul_f32_e32 v61, v53, v61
	v_cvt_pk_bf16_f32 v50, v54, v55
	v_cvt_pk_bf16_f32 v51, v56, v57
	v_cvt_pk_bf16_f32 v52, v58, v59
	v_cvt_pk_bf16_f32 v53, v60, v61
	v_mad_i64_i32 v[54:55], s[24:25], v66, s64, v[140:141]
	flat_store_dwordx4 v[54:55], v[50:53]
	s_mov_b64 s[24:25], -1
	s_nop 0
	v_add_u32_e32 v50, 0x90, v142
	s_cbranch_vccnz .LBB0_193
	s_cmp_eq_u32 s48, s12
	s_cbranch_scc1 .LBB0_190
	v_ashrrev_i32_e32 v51, 31, v50
	v_lshlrev_b64 v[52:53], 6, v[50:51]
	v_lshl_add_u64 v[64:65], s[38:39], 0, v[52:53]
	flat_load_dwordx4 v[52:55], v[64:65]
	flat_load_dwordx4 v[56:59], v[64:65] offset:16
	flat_load_dwordx4 v[60:63], v[64:65] offset:32
	s_nop 0
	flat_load_dwordx4 v[64:67], v[64:65] offset:48
	s_mov_b64 s[24:25], 0
	s_waitcnt vmcnt(0) lgkmcnt(0)
	v_mov_b32_e32 v68, v53
	v_mov_b32_e32 v69, v54
	v_mov_b32_e32 v53, v55
	v_mov_b32_e32 v54, v57
	v_mov_b32_e32 v55, v58
	v_mov_b32_e32 v57, v59
	v_pk_add_f32 v[52:53], v[68:69], v[52:53]
	v_pk_add_f32 v[54:55], v[54:55], v[56:57]
	v_pk_add_f32 v[52:53], v[52:53], v[52:53] op_sel:[0,1] op_sel_hi:[1,0]
	v_pk_add_f32 v[54:55], v[54:55], v[54:55] op_sel:[0,1] op_sel_hi:[1,0]
	v_add_f32_e32 v56, v60, v61
	v_add_f32_e32 v58, v62, v63
	v_mov_b32_e32 v53, v64
	v_mov_b32_e32 v55, v65
	v_mov_b32_e32 v57, v66
	v_mov_b32_e32 v59, v67
	v_pk_add_f32 v[52:53], v[52:53], v[54:55]
	v_pk_add_f32 v[54:55], v[56:57], v[58:59]
	s_nop 0
	v_pk_add_f32 v[52:53], v[52:53], v[54:55]
	s_nop 0
	v_add_f32_e32 v51, v52, v53
	v_fmamk_f32 v51, v51, 0x3a800000, v205
	v_cmp_gt_f32_e32 vcc, s77, v51
	v_mul_f32_e32 v52, 0x4b800000, v51
	s_nop 0
	v_cndmask_b32_e32 v51, v51, v52, vcc
	v_rsq_f32_e32 v51, v51
	s_nop 0
	v_mul_f32_e32 v52, 0x45800000, v51
	v_cndmask_b32_e32 v52, v51, v52, vcc

; __device__ __forceinline__ u32x4 pack8(f32x4 a, f32x4 b) { u32x4 w; w.x = pk2(a[0], a[1]); w.y = pk2(a[2], a[3]); w.z = pk2(b[0], b[1]); w.w = pk2(b[2], b[3]); return w; }
; __device__ __forceinline__ float fast_sigmoid(float x) { return __builtin_amdgcn_rcpf(1.0f + __builtin_amdgcn_exp2f(-x * LOG2E)); }
;     __device__ __forceinline__ void operator()(const Acc& acc, const Unit& u, int wr, int wc, int fr, int fq, const RsCtx& rc) const {
;     ...
;             for (int m = 0; m < 4; ++m) { const int row = EPI_ROW(u, ai, wr, m, fr); const float rs = rc.get(u.pm, ai * 128 + wr * 64 + m * 16 + fr, row);
;                 f32x4 a0 = acc[ai][0][m][0] * rs, a1 = acc[ai][0][m][1] * rs; const f32x4 b0 = acc[ai][1][m][0] * rs, b1 = acc[ai][1][m][1] * rs;
; #pragma unroll
;                 for (int e = 0; e < 4; ++e) { a0[e] = a0[e] * fast_sigmoid(a0[e]) * b0[e]; a1[e] = a1[e] * fast_sigmoid(a1[e]) * b1[e]; }
;                 *(u32x4*)(O + (size_t)row * FF + col) = pack8(a0, a1);
.LBB0_195:
	s_waitcnt lgkmcnt(0)
	s_and_b64 vcc, exec, s[6:7]
	s_mov_b32 s100, 0xbfb8aa3b
	v_mul_f32_e32 v46, v52, v46
	v_mul_f32_e32 v47, v52, v47
	v_mul_f32_e32 v48, v52, v48
	v_mul_f32_e32 v49, v52, v49
	v_mul_f32_e32 v42, v52, v42
	v_mul_f32_e32 v43, v52, v43
	v_mul_f32_e32 v44, v52, v44
	v_mul_f32_e32 v45, v52, v45
	v_mul_f32_e32 v54, s100, v46
	v_mul_f32_e32 v55, s100, v47
	v_mul_f32_e32 v56, s100, v48
	v_mul_f32_e32 v57, s100, v49
	v_mul_f32_e32 v58, s100, v42
	v_mul_f32_e32 v59, s100, v43
	v_mul_f32_e32 v60, s100, v44
	v_mul_f32_e32 v61, s100, v45
	v_exp_f32_e32 v54, v54
	v_exp_f32_e32 v55, v55
	v_exp_f32_e32 v56, v56
	v_exp_f32_e32 v57, v57
	v_exp_f32_e32 v58, v58
	v_exp_f32_e32 v59, v59
	v_exp_f32_e32 v60, v60
	v_exp_f32_e32 v61, v61
	v_mul_f32_e32 v38, v52, v38
	v_mul_f32_e32 v39, v52, v39
	v_mul_f32_e32 v40, v52, v40
	v_mul_f32_e32 v41, v52, v41
	v_mul_f32_e32 v34, v52, v34
	v_mul_f32_e32 v35, v52, v35
	v_mul_f32_e32 v36, v52, v36
	v_mul_f32_e32 v37, v52, v37
	v_add_f32_e32 v54, 1.0, v54
	v_add_f32_e32 v55, 1.0, v55
	v_add_f32_e32 v56, 1.0, v56
	v_add_f32_e32 v57, 1.0, v57
	v_add_f32_e32 v58, 1.0, v58
	v_add_f32_e32 v59, 1.0, v59
	v_add_f32_e32 v60, 1.0, v60
	v_add_f32_e32 v61, 1.0, v61
	v_rcp_f32_e32 v54, v54
	v_rcp_f32_e32 v55, v55
	v_rcp_f32_e32 v56, v56
	v_rcp_f32_e32 v57, v57
	v_rcp_f32_e32 v58, v58
	v_rcp_f32_e32 v59, v59
	v_rcp_f32_e32 v60, v60
	v_rcp_f32_e32 v61, v61
	v_mul_f32_e32 v46, v46, v54
	v_mul_f32_e32 v47, v47, v55
	v_mul_f32_e32 v48, v48, v56
	v_mul_f32_e32 v49, v49, v57
	v_mul_f32_e32 v42, v42, v58
	v_mul_f32_e32 v43, v43, v59
	v_mul_f32_e32 v44, v44, v60
	v_mul_f32_e32 v45, v45, v61
	v_mul_f32_e32 v38, v38, v46
	v_mul_f32_e32 v39, v39, v47
	v_mul_f32_e32 v40, v40, v48
	v_mul_f32_e32 v41, v41, v49
	v_mul_f32_e32 v42, v34, v42
	v_mul_f32_e32 v43, v35, v43
	v_mul_f32_e32 v44, v36, v44
	v_mul_f32_e32 v45, v37, v45
	v_cvt_pk_bf16_f32 v34, v38, v39
	v_cvt_pk_bf16_f32 v35, v40, v41
	v_cvt_pk_bf16_f32 v36, v42, v43
	v_cvt_pk_bf16_f32 v37, v44, v45
	v_mad_i64_i32 v[38:39], s[24:25], v50, s64, v[140:141]
	flat_store_dwordx4 v[38:39], v[34:37]
	s_mov_b64 s[24:25], -1
	s_nop 0
	v_add_u32_e32 v34, 0xa0, v142
	s_cbranch_vccnz .LBB0_201
	s_cmp_eq_u32 s48, s12
	s_cbranch_scc1 .LBB0_198
	v_ashrrev_i32_e32 v35, 31, v34
	v_lshlrev_b64 v[36:37], 6, v[34:35]
	v_lshl_add_u64 v[48:49], s[38:39], 0, v[36:37]
	flat_load_dwordx4 v[36:39], v[48:49]
	flat_load_dwordx4 v[40:43], v[48:49] offset:16
	flat_load_dwordx4 v[44:47], v[48:49] offset:32
	s_nop 0
	flat_load_dwordx4 v[48:51], v[48:49] offset:48
	s_mov_b64 s[24:25], 0
	s_waitcnt vmcnt(0) lgkmcnt(0)
	v_mov_b32_e32 v52, v37
	v_mov_b32_e32 v53, v38
	v_mov_b32_e32 v37, v39
	v_mov_b32_e32 v38, v41
	v_mov_b32_e32 v39, v42
	v_mov_b32_e32 v41, v43
	v_pk_add_f32 v[36:37], v[52:53], v[36:37]
	v_pk_add_f32 v[38:39], v[38:39], v[40:41]
	v_pk_add_f32 v[36:37], v[36:37], v[36:37] op_sel:[0,1] op_sel_hi:[1,0]
	v_pk_add_f32 v[38:39], v[38:39], v[38:39] op_sel:[0,1] op_sel_hi:[1,0]
	v_add_f32_e32 v40, v44, v45
	v_add_f32_e32 v42, v46, v47
	v_mov_b32_e32 v37, v48
	v_mov_b32_e32 v39, v49
	v_mov_b32_e32 v41, v50
	v_mov_b32_e32 v43, v51
	v_pk_add_f32 v[36:37], v[36:37], v[38:39]
	v_pk_add_f32 v[38:39], v[40:41], v[42:43]
	s_nop 0
	v_pk_add_f32 v[36:37], v[36:37], v[38:39]
	s_nop 0
	v_add_f32_e32 v35, v36, v37
	v_fmamk_f32 v35, v35, 0x3a800000, v205
	v_cmp_gt_f32_e32 vcc, s77, v35
	v_mul_f32_e32 v36, 0x4b800000, v35
	s_nop 0
	v_cndmask_b32_e32 v35, v35, v36, vcc
	v_rsq_f32_e32 v35, v35
	s_nop 0
	v_mul_f32_e32 v36, 0x45800000, v35
	v_cndmask_b32_e32 v36, v35, v36, vcc

; __device__ __forceinline__ u32x4 pack8(f32x4 a, f32x4 b) { u32x4 w; w.x = pk2(a[0], a[1]); w.y = pk2(a[2], a[3]); w.z = pk2(b[0], b[1]); w.w = pk2(b[2], b[3]); return w; }
; __device__ __forceinline__ float fast_sigmoid(float x) { return __builtin_amdgcn_rcpf(1.0f + __builtin_amdgcn_exp2f(-x * LOG2E)); }
;     __device__ __forceinline__ void operator()(const Acc& acc, const Unit& u, int wr, int wc, int fr, int fq, const RsCtx& rc) const {
;     ...
;             for (int m = 0; m < 4; ++m) { const int row = EPI_ROW(u, ai, wr, m, fr); const float rs = rc.get(u.pm, ai * 128 + wr * 64 + m * 16 + fr, row);
;                 f32x4 a0 = acc[ai][0][m][0] * rs, a1 = acc[ai][0][m][1] * rs; const f32x4 b0 = acc[ai][1][m][0] * rs, b1 = acc[ai][1][m][1] * rs;
; #pragma unroll
;                 for (int e = 0; e < 4; ++e) { a0[e] = a0[e] * fast_sigmoid(a0[e]) * b0[e]; a1[e] = a1[e] * fast_sigmoid(a1[e]) * b1[e]; }
;                 *(u32x4*)(O + (size_t)row * FF + col) = pack8(a0, a1);
.LBB0_203:
	s_waitcnt lgkmcnt(0)
	s_and_b64 vcc, exec, s[6:7]
	s_mov_b32 s100, 0xbfb8aa3b
	v_mul_f32_e32 v30, v36, v30
	v_mul_f32_e32 v31, v36, v31
	v_mul_f32_e32 v32, v36, v32
	v_mul_f32_e32 v33, v36, v33
	v_mul_f32_e32 v26, v36, v26
	v_mul_f32_e32 v27, v36, v27
	v_mul_f32_e32 v28, v36, v28
	v_mul_f32_e32 v29, v36, v29
	v_mul_f32_e32 v38, s100, v30
	v_mul_f32_e32 v39, s100, v31
	v_mul_f32_e32 v40, s100, v32
	v_mul_f32_e32 v41, s100, v33
	v_mul_f32_e32 v42, s100, v26
	v_mul_f32_e32 v43, s100, v27
	v_mul_f32_e32 v44, s100, v28
	v_mul_f32_e32 v45, s100, v29
	v_exp_f32_e32 v38, v38
	v_exp_f32_e32 v39, v39
	v_exp_f32_e32 v40, v40
	v_exp_f32_e32 v41, v41
	v_exp_f32_e32 v42, v42
	v_exp_f32_e32 v43, v43
	v_exp_f32_e32 v44, v44
	v_exp_f32_e32 v45, v45
	v_mul_f32_e32 v22, v36, v22
	v_mul_f32_e32 v23, v36, v23
	v_mul_f32_e32 v24, v36, v24
	v_mul_f32_e32 v25, v36, v25
	v_mul_f32_e32 v18, v36, v18
	v_mul_f32_e32 v19, v36, v19
	v_mul_f32_e32 v20, v36, v20
	v_mul_f32_e32 v21, v36, v21
	v_add_f32_e32 v38, 1.0, v38
	v_add_f32_e32 v39, 1.0, v39
	v_add_f32_e32 v40, 1.0, v40
	v_add_f32_e32 v41, 1.0, v41
	v_add_f32_e32 v42, 1.0, v42
	v_add_f32_e32 v43, 1.0, v43
	v_add_f32_e32 v44, 1.0, v44
	v_add_f32_e32 v45, 1.0, v45
	v_rcp_f32_e32 v38, v38
	v_rcp_f32_e32 v39, v39
	v_rcp_f32_e32 v40, v40
	v_rcp_f32_e32 v41, v41
	v_rcp_f32_e32 v42, v42
	v_rcp_f32_e32 v43, v43
	v_rcp_f32_e32 v44, v44
	v_rcp_f32_e32 v45, v45
	v_mul_f32_e32 v30, v30, v38
	v_mul_f32_e32 v31, v31, v39
	v_mul_f32_e32 v32, v32, v40
	v_mul_f32_e32 v33, v33, v41
	v_mul_f32_e32 v26, v26, v42
	v_mul_f32_e32 v27, v27, v43
	v_mul_f32_e32 v28, v28, v44
	v_mul_f32_e32 v29, v29, v45
	v_mul_f32_e32 v22, v22, v30
	v_mul_f32_e32 v23, v23, v31
	v_mul_f32_e32 v24, v24, v32
	v_mul_f32_e32 v25, v25, v33
	v_mul_f32_e32 v26, v18, v26
	v_mul_f32_e32 v27, v19, v27
	v_mul_f32_e32 v28, v20, v28
	v_mul_f32_e32 v29, v21, v29
	v_cvt_pk_bf16_f32 v18, v22, v23
	v_cvt_pk_bf16_f32 v19, v24, v25
	v_cvt_pk_bf16_f32 v20, v26, v27
	v_cvt_pk_bf16_f32 v21, v28, v29
	v_mad_i64_i32 v[22:23], s[24:25], v34, s64, v[140:141]
	flat_store_dwordx4 v[22:23], v[18:21]
	s_mov_b64 s[24:25], -1
	s_nop 0
	v_add_u32_e32 v18, 0xb0, v142
	s_cbranch_vccnz .LBB0_209
	s_cmp_eq_u32 s48, s12
	s_mov_b64 s[6:7], -1
	s_cbranch_scc1 .LBB0_206
	v_ashrrev_i32_e32 v19, 31, v18
	v_lshlrev_b64 v[20:21], 6, v[18:19]
	v_lshl_add_u64 v[32:33], s[38:39], 0, v[20:21]
	flat_load_dwordx4 v[20:23], v[32:33]
	flat_load_dwordx4 v[24:27], v[32:33] offset:16
	flat_load_dwordx4 v[28:31], v[32:33] offset:32
	s_nop 0
	flat_load_dwordx4 v[32:35], v[32:33] offset:48
	s_mov_b64 s[6:7], 0
	s_waitcnt vmcnt(0) lgkmcnt(0)
	v_mov_b32_e32 v36, v21
	v_mov_b32_e32 v37, v22
	v_mov_b32_e32 v21, v23
	v_mov_b32_e32 v22, v25
	v_mov_b32_e32 v23, v26
	v_mov_b32_e32 v25, v27
	v_pk_add_f32 v[20:21], v[36:37], v[20:21]
	v_pk_add_f32 v[22:23], v[22:23], v[24:25]
	v_pk_add_f32 v[20:21], v[20:21], v[20:21] op_sel:[0,1] op_sel_hi:[1,0]
	v_pk_add_f32 v[22:23], v[22:23], v[22:23] op_sel:[0,1] op_sel_hi:[1,0]
	v_add_f32_e32 v24, v28, v29
	v_add_f32_e32 v26, v30, v31
	v_mov_b32_e32 v21, v32
	v_mov_b32_e32 v23, v33
	v_mov_b32_e32 v25, v34
	v_mov_b32_e32 v27, v35
	v_pk_add_f32 v[20:21], v[20:21], v[22:23]
	v_pk_add_f32 v[22:23], v[24:25], v[26:27]
	s_nop 0
	v_pk_add_f32 v[20:21], v[20:21], v[22:23]
	s_nop 0
	v_add_f32_e32 v19, v20, v21
	v_fmamk_f32 v19, v19, 0x3a800000, v205
	v_cmp_gt_f32_e32 vcc, s77, v19
	v_mul_f32_e32 v20, 0x4b800000, v19
	s_nop 0
	v_cndmask_b32_e32 v19, v19, v20, vcc
	v_rsq_f32_e32 v19, v19
	s_nop 0
	v_mul_f32_e32 v20, 0x45800000, v19
	v_cndmask_b32_e32 v20, v19, v20, vcc

; __device__ __forceinline__ u32x4 pack8(f32x4 a, f32x4 b) { u32x4 w; w.x = pk2(a[0], a[1]); w.y = pk2(a[2], a[3]); w.z = pk2(b[0], b[1]); w.w = pk2(b[2], b[3]); return w; }
; __device__ __forceinline__ float fast_sigmoid(float x) { return __builtin_amdgcn_rcpf(1.0f + __builtin_amdgcn_exp2f(-x * LOG2E)); }
; #define PG8_BAR __builtin_amdgcn_s_barrier()
; #define PG8_BAR __builtin_amdgcn_s_barrier()
; template <class Epi, class Sched>
; __device__ __forceinline__ void gemm_phase(LAS unsigned char* lds, const Gemm g, const Sched S, const Epi E, const int tid) {
;     ...
;         if (!has_next) break;
; #pragma unroll
;         for (int a = 0; a < 2; ++a)
; #pragma unroll
;             for (int b = 0; b < 2; ++b)
; #pragma unroll
;                 for (int m = 0; m < 4; ++m)
; #pragma unroll
;                     for (int n = 0; n < 2; ++n) acc[a][b][m][n] = (f32x4){0.f, 0.f, 0.f, 0.f};
;         cur = nxt; cA = nA; cB = nB; ++ui;
;         if (wr == 1) PG8_BAR;
;     __device__ __forceinline__ void operator()(const Acc& acc, const Unit& u, int wr, int wc, int fr, int fq, const RsCtx& rc) const {
;     ...
;             for (int m = 0; m < 4; ++m) { const int row = EPI_ROW(u, ai, wr, m, fr); const float rs = rc.get(u.pm, ai * 128 + wr * 64 + m * 16 + fr, row);
;                 f32x4 a0 = acc[ai][0][m][0] * rs, a1 = acc[ai][0][m][1] * rs; const f32x4 b0 = acc[ai][1][m][0] * rs, b1 = acc[ai][1][m][1] * rs;
; #pragma unroll
;                 for (int e = 0; e < 4; ++e) { a0[e] = a0[e] * fast_sigmoid(a0[e]) * b0[e]; a1[e] = a1[e] * fast_sigmoid(a1[e]) * b1[e]; }
;                 *(u32x4*)(O + (size_t)row * FF + col) = pack8(a0, a1);
.LBB0_211:
	s_waitcnt lgkmcnt(0)
	s_andn2_b64 vcc, exec, s[4:5]
	s_mov_b32 s100, 0xbfb8aa3b
	v_mul_f32_e32 v14, v20, v14
	v_mul_f32_e32 v15, v20, v15
	v_mul_f32_e32 v16, v20, v16
	v_mul_f32_e32 v17, v20, v17
	v_mul_f32_e32 v10, v20, v10
	v_mul_f32_e32 v11, v20, v11
	v_mul_f32_e32 v12, v20, v12
	v_mul_f32_e32 v13, v20, v13
	v_mul_f32_e32 v22, s100, v14
	v_mul_f32_e32 v23, s100, v15
	v_mul_f32_e32 v24, s100, v16
	v_mul_f32_e32 v25, s100, v17
	v_mul_f32_e32 v26, s100, v10
	v_mul_f32_e32 v27, s100, v11
	v_mul_f32_e32 v28, s100, v12
	v_mul_f32_e32 v29, s100, v13
	v_exp_f32_e32 v22, v22
	v_exp_f32_e32 v23, v23
	v_exp_f32_e32 v24, v24
	v_exp_f32_e32 v25, v25
	v_exp_f32_e32 v26, v26
	v_exp_f32_e32 v27, v27
	v_exp_f32_e32 v28, v28
	v_exp_f32_e32 v29, v29
	v_mul_f32_e32 v6, v20, v6
	v_mul_f32_e32 v7, v20, v7
	v_mul_f32_e32 v8, v20, v8
	v_mul_f32_e32 v9, v20, v9
	v_mul_f32_e32 v2, v20, v2
	v_mul_f32_e32 v3, v20, v3
	v_mul_f32_e32 v4, v20, v4
	v_mul_f32_e32 v5, v20, v5
	v_add_f32_e32 v22, 1.0, v22
	v_add_f32_e32 v23, 1.0, v23
	v_add_f32_e32 v24, 1.0, v24
	v_add_f32_e32 v25, 1.0, v25
	v_add_f32_e32 v26, 1.0, v26
	v_add_f32_e32 v27, 1.0, v27
	v_add_f32_e32 v28, 1.0, v28
	v_add_f32_e32 v29, 1.0, v29
	v_rcp_f32_e32 v22, v22
	v_rcp_f32_e32 v23, v23
	v_rcp_f32_e32 v24, v24
	v_rcp_f32_e32 v25, v25
	v_rcp_f32_e32 v26, v26
	v_rcp_f32_e32 v27, v27
	v_rcp_f32_e32 v28, v28
	v_rcp_f32_e32 v29, v29
	v_mul_f32_e32 v14, v14, v22
	v_mul_f32_e32 v15, v15, v23
	v_mul_f32_e32 v16, v16, v24
	v_mul_f32_e32 v17, v17, v25
	v_mul_f32_e32 v10, v10, v26
	v_mul_f32_e32 v11, v11, v27
	v_mul_f32_e32 v12, v12, v28
	v_mul_f32_e32 v13, v13, v29
	v_mul_f32_e32 v6, v6, v14
	v_mul_f32_e32 v7, v7, v15
	v_mul_f32_e32 v8, v8, v16
	v_mul_f32_e32 v9, v9, v17
	v_mul_f32_e32 v10, v2, v10
	v_mul_f32_e32 v11, v3, v11
	v_mul_f32_e32 v12, v4, v12
	v_mul_f32_e32 v13, v5, v13
	v_cvt_pk_bf16_f32 v2, v6, v7
	v_cvt_pk_bf16_f32 v3, v8, v9
	v_cvt_pk_bf16_f32 v4, v10, v11
	v_cvt_pk_bf16_f32 v5, v12, v13
	v_mad_i64_i32 v[6:7], s[6:7], v18, s64, v[140:141]
	flat_store_dwordx4 v[6:7], v[2:5]
	s_mov_b64 s[6:7], -1
	s_cbranch_vccnz .LBB0_138
	s_andn2_b64 vcc, exec, s[8:9]
	s_cbranch_vccnz .LBB0_137
	s_barrier
	s_branch .LBB0_137
